# SSD inter-chunk scan inner loop software-pipelined by hand (next 8 chunks requested before the current 8 are scanned and stored)
# speedup vs baseline: 1.0049x; 1.0049x over previous
; __device__ __forceinline__ unsigned pk2(float lo, float hi) { const cvt_f2 v = {lo, hi}; const cvt_b2 r = __builtin_convertvector(v, cvt_b2); return __builtin_bit_cast(unsigned, r); }
; __device__ __forceinline__ void ssd_scan_phase(Frame& F, bool dry) {
;     ...
;     for (int i4 = blockIdx.x * NTHREADS + F.tid; i4 < 64 * 64 * 128 / 4; i4 += F.G * NTHREADS) {
;         const int h = i4 >> 11; bf16* p = ST + (size_t)i4 * 4; bf16* pd = DS + (size_t)i4 * 4; float r0 = 0.f, r1 = 0.f, r2 = 0.f, r3 = 0.f;
; #pragma unroll 1
;         for (int c0 = 0; c0 < 256; c0 += 8) {
;             v2u loc[8]; float dc[8];
; #pragma unroll
;             for (int i = 0; i < 8; ++i) { loc[i] = *(const v2u*)(p + (size_t)(c0 + i) * 524288); dc[i] = CD[(c0 + i) * 64 + h]; }
; #pragma unroll
;             for (int i = 0; i < 8; ++i) { v2u o; o.x = pk2(r0, r1); o.y = pk2(r2, r3); *(v2u*)(pd + (size_t)((c0 + i) & cmask) * 524288) = o;
;                 r0 = r0 * dc[i] + bflo(loc[i].x); r1 = r1 * dc[i] + bfhi(loc[i].x); r2 = r2 * dc[i] + bflo(loc[i].y); r3 = r3 * dc[i] + bfhi(loc[i].y); }
;         }
.LBB0_1276:
	v_ashrrev_i32_e32 v12, 11, v6
	v_ashrrev_i32_e32 v13, 31, v12
	v_lshlrev_b64 v[14:15], 2, v[12:13]
	s_mov_b32 s18, -8
	v_mov_b64_e32 v[16:17], v[8:9]
	s_waitcnt lgkmcnt(0)
	v_mov_b32_e32 v4, 0
	v_mov_b32_e32 v5, v11
	v_mov_b32_e32 v2, 0
	v_mov_b32_e32 v3, v11
	s_mov_b64 s[20:21], 0x34000000
	s_mov_b64 s[22:23], 0x100000
	s_mov_b64 s[24:25], 0x44500000
	s_mov_b32 s18, 0
	v_lshl_add_u64 v[18:19], s[86:87], 0, v[16:17]
	v_lshl_add_u64 v[72:73], v[18:19], 0, s[20:21]
	v_lshl_add_u64 v[74:75], v[72:73], 0, s[22:23]
	v_lshl_add_u64 v[76:77], v[74:75], 0, s[22:23]
	v_lshl_add_u64 v[78:79], v[76:77], 0, s[22:23]
	v_lshl_add_u64 v[80:81], v[78:79], 0, s[22:23]
	v_lshl_add_u64 v[82:83], v[80:81], 0, s[22:23]
	v_lshl_add_u64 v[84:85], v[82:83], 0, s[22:23]
	v_lshl_add_u64 v[86:87], v[84:85], 0, s[22:23]
	v_lshl_add_u64 v[20:21], s[86:87], 0, v[14:15]
	v_lshl_add_u64 v[20:21], v[20:21], 0, s[24:25]
	global_load_dwordx2 v[24:25], v[72:73], off
	global_load_dwordx2 v[26:27], v[74:75], off
	global_load_dwordx2 v[28:29], v[76:77], off
	global_load_dwordx2 v[30:31], v[78:79], off
	global_load_dwordx2 v[32:33], v[80:81], off
	global_load_dwordx2 v[34:35], v[82:83], off
	global_load_dwordx2 v[36:37], v[84:85], off
	global_load_dwordx2 v[38:39], v[86:87], off
	global_load_dword v40, v[20:21], off
	global_load_dword v42, v[20:21], off offset:256
	global_load_dword v44, v[20:21], off offset:512
	global_load_dword v46, v[20:21], off offset:768
	global_load_dword v48, v[20:21], off offset:1024
	global_load_dword v50, v[20:21], off offset:1280
	global_load_dword v52, v[20:21], off offset:1536
	global_load_dword v54, v[20:21], off offset:1792
.Lp8_loop:
	v_lshl_add_u64 v[16:17], v[16:17], 0, s[14:15]
	v_lshl_add_u64 v[14:15], v[14:15], 0, s[12:13]
	v_lshl_add_u64 v[18:19], s[86:87], 0, v[16:17]
	v_lshl_add_u64 v[88:89], v[18:19], 0, s[20:21]
	v_lshl_add_u64 v[90:91], v[88:89], 0, s[22:23]
	v_lshl_add_u64 v[92:93], v[90:91], 0, s[22:23]
	v_lshl_add_u64 v[94:95], v[92:93], 0, s[22:23]
	v_lshl_add_u64 v[96:97], v[94:95], 0, s[22:23]
	v_lshl_add_u64 v[98:99], v[96:97], 0, s[22:23]
	v_lshl_add_u64 v[100:101], v[98:99], 0, s[22:23]
	v_lshl_add_u64 v[102:103], v[100:101], 0, s[22:23]
	v_lshl_add_u64 v[20:21], s[86:87], 0, v[14:15]
	v_lshl_add_u64 v[20:21], v[20:21], 0, s[24:25]
	global_load_dwordx2 v[56:57], v[88:89], off
	global_load_dwordx2 v[58:59], v[90:91], off
	global_load_dwordx2 v[60:61], v[92:93], off
	global_load_dwordx2 v[62:63], v[94:95], off
	global_load_dwordx2 v[64:65], v[96:97], off
	global_load_dwordx2 v[66:67], v[98:99], off
	global_load_dwordx2 v[68:69], v[100:101], off
	global_load_dwordx2 v[70:71], v[102:103], off
	global_load_dword v104, v[20:21], off
	global_load_dword v106, v[20:21], off offset:256
	global_load_dword v108, v[20:21], off offset:512
	global_load_dword v110, v[20:21], off offset:768
	global_load_dword v112, v[20:21], off offset:1024
	global_load_dword v114, v[20:21], off offset:1280
	global_load_dword v116, v[20:21], off offset:1536
	global_load_dword v118, v[20:21], off offset:1792
	s_waitcnt vmcnt(16)
	v_cvt_pk_bf16_f32 v120, v2, v3
	v_cvt_pk_bf16_f32 v121, v4, v5
	global_store_dwordx2 v[72:73], v[120:121], off
	v_lshlrev_b32_e32 v124, 16, v24
	v_and_b32_e32 v125, 0xffff0000, v24
	v_lshlrev_b32_e32 v126, 16, v25
	v_and_b32_e32 v127, 0xffff0000, v25
	v_pk_fma_f32 v[2:3], v[40:41], v[2:3], v[124:125] op_sel_hi:[0,1,1]
	v_pk_fma_f32 v[4:5], v[40:41], v[4:5], v[126:127] op_sel_hi:[0,1,1]
	v_cvt_pk_bf16_f32 v122, v2, v3
	v_cvt_pk_bf16_f32 v123, v4, v5
	global_store_dwordx2 v[74:75], v[122:123], off
	v_lshlrev_b32_e32 v124, 16, v26
	v_and_b32_e32 v125, 0xffff0000, v26
	v_lshlrev_b32_e32 v126, 16, v27
	v_and_b32_e32 v127, 0xffff0000, v27
	v_pk_fma_f32 v[2:3], v[42:43], v[2:3], v[124:125] op_sel_hi:[0,1,1]
	v_pk_fma_f32 v[4:5], v[42:43], v[4:5], v[126:127] op_sel_hi:[0,1,1]
	v_cvt_pk_bf16_f32 v120, v2, v3
	v_cvt_pk_bf16_f32 v121, v4, v5
	global_store_dwordx2 v[76:77], v[120:121], off
	v_lshlrev_b32_e32 v124, 16, v28
	v_and_b32_e32 v125, 0xffff0000, v28
	v_lshlrev_b32_e32 v126, 16, v29
	v_and_b32_e32 v127, 0xffff0000, v29
	v_pk_fma_f32 v[2:3], v[44:45], v[2:3], v[124:125] op_sel_hi:[0,1,1]
	v_pk_fma_f32 v[4:5], v[44:45], v[4:5], v[126:127] op_sel_hi:[0,1,1]
	v_cvt_pk_bf16_f32 v122, v2, v3
	v_cvt_pk_bf16_f32 v123, v4, v5
	global_store_dwordx2 v[78:79], v[122:123], off
	v_lshlrev_b32_e32 v124, 16, v30
	v_and_b32_e32 v125, 0xffff0000, v30
	v_lshlrev_b32_e32 v126, 16, v31
	v_and_b32_e32 v127, 0xffff0000, v31
	v_pk_fma_f32 v[2:3], v[46:47], v[2:3], v[124:125] op_sel_hi:[0,1,1]
	v_pk_fma_f32 v[4:5], v[46:47], v[4:5], v[126:127] op_sel_hi:[0,1,1]
	v_cvt_pk_bf16_f32 v120, v2, v3
	v_cvt_pk_bf16_f32 v121, v4, v5
	global_store_dwordx2 v[80:81], v[120:121], off
	v_lshlrev_b32_e32 v124, 16, v32
	v_and_b32_e32 v125, 0xffff0000, v32
	v_lshlrev_b32_e32 v126, 16, v33
	v_and_b32_e32 v127, 0xffff0000, v33
	v_pk_fma_f32 v[2:3], v[48:49], v[2:3], v[124:125] op_sel_hi:[0,1,1]
	v_pk_fma_f32 v[4:5], v[48:49], v[4:5], v[126:127] op_sel_hi:[0,1,1]
	v_cvt_pk_bf16_f32 v122, v2, v3
	v_cvt_pk_bf16_f32 v123, v4, v5
	global_store_dwordx2 v[82:83], v[122:123], off
	v_lshlrev_b32_e32 v124, 16, v34
	v_and_b32_e32 v125, 0xffff0000, v34
	v_lshlrev_b32_e32 v126, 16, v35
	v_and_b32_e32 v127, 0xffff0000, v35
	v_pk_fma_f32 v[2:3], v[50:51], v[2:3], v[124:125] op_sel_hi:[0,1,1]
	v_pk_fma_f32 v[4:5], v[50:51], v[4:5], v[126:127] op_sel_hi:[0,1,1]
	v_cvt_pk_bf16_f32 v120, v2, v3
	v_cvt_pk_bf16_f32 v121, v4, v5
	global_store_dwordx2 v[84:85], v[120:121], off
	v_lshlrev_b32_e32 v124, 16, v36
	v_and_b32_e32 v125, 0xffff0000, v36
	v_lshlrev_b32_e32 v126, 16, v37
	v_and_b32_e32 v127, 0xffff0000, v37
	v_pk_fma_f32 v[2:3], v[52:53], v[2:3], v[124:125] op_sel_hi:[0,1,1]
	v_pk_fma_f32 v[4:5], v[52:53], v[4:5], v[126:127] op_sel_hi:[0,1,1]
	v_cvt_pk_bf16_f32 v122, v2, v3
	v_cvt_pk_bf16_f32 v123, v4, v5
	global_store_dwordx2 v[86:87], v[122:123], off
	v_lshlrev_b32_e32 v124, 16, v38
	v_and_b32_e32 v125, 0xffff0000, v38
	v_lshlrev_b32_e32 v126, 16, v39
	v_and_b32_e32 v127, 0xffff0000, v39
	v_pk_fma_f32 v[2:3], v[54:55], v[2:3], v[124:125] op_sel_hi:[0,1,1]
	v_pk_fma_f32 v[4:5], v[54:55], v[4:5], v[126:127] op_sel_hi:[0,1,1]
	s_cmp_eq_u32 s18, 15
	s_cbranch_scc1 .Lp8_last
; __device__ __forceinline__ unsigned pk2(float lo, float hi) { const cvt_f2 v = {lo, hi}; const cvt_b2 r = __builtin_convertvector(v, cvt_b2); return __builtin_bit_cast(unsigned, r); }
; __device__ __forceinline__ void ssd_scan_phase(Frame& F, bool dry) {
;     ...
;         for (int c0 = 0; c0 < 256; c0 += 8) {
;             v2u loc[8]; float dc[8];
; #pragma unroll
;             for (int i = 0; i < 8; ++i) { loc[i] = *(const v2u*)(p + (size_t)(c0 + i) * 524288); dc[i] = CD[(c0 + i) * 64 + h]; }
; #pragma unroll
;             for (int i = 0; i < 8; ++i) { v2u o; o.x = pk2(r0, r1); o.y = pk2(r2, r3); *(v2u*)(pd + (size_t)((c0 + i) & cmask) * 524288) = o;
;                 r0 = r0 * dc[i] + bflo(loc[i].x); r1 = r1 * dc[i] + bfhi(loc[i].x); r2 = r2 * dc[i] + bflo(loc[i].y); r3 = r3 * dc[i] + bfhi(loc[i].y); }
;         }
	v_lshl_add_u64 v[16:17], v[16:17], 0, s[14:15]
	v_lshl_add_u64 v[14:15], v[14:15], 0, s[12:13]
	v_lshl_add_u64 v[18:19], s[86:87], 0, v[16:17]
	v_lshl_add_u64 v[72:73], v[18:19], 0, s[20:21]
	v_lshl_add_u64 v[74:75], v[72:73], 0, s[22:23]
	v_lshl_add_u64 v[76:77], v[74:75], 0, s[22:23]
	v_lshl_add_u64 v[78:79], v[76:77], 0, s[22:23]
	v_lshl_add_u64 v[80:81], v[78:79], 0, s[22:23]
	v_lshl_add_u64 v[82:83], v[80:81], 0, s[22:23]
	v_lshl_add_u64 v[84:85], v[82:83], 0, s[22:23]
	v_lshl_add_u64 v[86:87], v[84:85], 0, s[22:23]
	v_lshl_add_u64 v[20:21], s[86:87], 0, v[14:15]
	v_lshl_add_u64 v[20:21], v[20:21], 0, s[24:25]
	global_load_dwordx2 v[24:25], v[72:73], off
	global_load_dwordx2 v[26:27], v[74:75], off
	global_load_dwordx2 v[28:29], v[76:77], off
	global_load_dwordx2 v[30:31], v[78:79], off
	global_load_dwordx2 v[32:33], v[80:81], off
	global_load_dwordx2 v[34:35], v[82:83], off
	global_load_dwordx2 v[36:37], v[84:85], off
	global_load_dwordx2 v[38:39], v[86:87], off
	global_load_dword v40, v[20:21], off
	global_load_dword v42, v[20:21], off offset:256
	global_load_dword v44, v[20:21], off offset:512
	global_load_dword v46, v[20:21], off offset:768
	global_load_dword v48, v[20:21], off offset:1024
	global_load_dword v50, v[20:21], off offset:1280
	global_load_dword v52, v[20:21], off offset:1536
	global_load_dword v54, v[20:21], off offset:1792
	s_waitcnt vmcnt(16)
	v_cvt_pk_bf16_f32 v120, v2, v3
	v_cvt_pk_bf16_f32 v121, v4, v5
	global_store_dwordx2 v[88:89], v[120:121], off
	v_lshlrev_b32_e32 v124, 16, v56
	v_and_b32_e32 v125, 0xffff0000, v56
	v_lshlrev_b32_e32 v126, 16, v57
	v_and_b32_e32 v127, 0xffff0000, v57
	v_pk_fma_f32 v[2:3], v[104:105], v[2:3], v[124:125] op_sel_hi:[0,1,1]
	v_pk_fma_f32 v[4:5], v[104:105], v[4:5], v[126:127] op_sel_hi:[0,1,1]
	v_cvt_pk_bf16_f32 v122, v2, v3
	v_cvt_pk_bf16_f32 v123, v4, v5
	global_store_dwordx2 v[90:91], v[122:123], off
	v_lshlrev_b32_e32 v124, 16, v58
	v_and_b32_e32 v125, 0xffff0000, v58
	v_lshlrev_b32_e32 v126, 16, v59
	v_and_b32_e32 v127, 0xffff0000, v59
	v_pk_fma_f32 v[2:3], v[106:107], v[2:3], v[124:125] op_sel_hi:[0,1,1]
	v_pk_fma_f32 v[4:5], v[106:107], v[4:5], v[126:127] op_sel_hi:[0,1,1]
	v_cvt_pk_bf16_f32 v120, v2, v3
	v_cvt_pk_bf16_f32 v121, v4, v5
	global_store_dwordx2 v[92:93], v[120:121], off
	v_lshlrev_b32_e32 v124, 16, v60
	v_and_b32_e32 v125, 0xffff0000, v60
	v_lshlrev_b32_e32 v126, 16, v61
	v_and_b32_e32 v127, 0xffff0000, v61
	v_pk_fma_f32 v[2:3], v[108:109], v[2:3], v[124:125] op_sel_hi:[0,1,1]
	v_pk_fma_f32 v[4:5], v[108:109], v[4:5], v[126:127] op_sel_hi:[0,1,1]
	v_cvt_pk_bf16_f32 v122, v2, v3
	v_cvt_pk_bf16_f32 v123, v4, v5
	global_store_dwordx2 v[94:95], v[122:123], off
	v_lshlrev_b32_e32 v124, 16, v62
	v_and_b32_e32 v125, 0xffff0000, v62
	v_lshlrev_b32_e32 v126, 16, v63
	v_and_b32_e32 v127, 0xffff0000, v63
	v_pk_fma_f32 v[2:3], v[110:111], v[2:3], v[124:125] op_sel_hi:[0,1,1]
	v_pk_fma_f32 v[4:5], v[110:111], v[4:5], v[126:127] op_sel_hi:[0,1,1]
	v_cvt_pk_bf16_f32 v120, v2, v3
	v_cvt_pk_bf16_f32 v121, v4, v5
	global_store_dwordx2 v[96:97], v[120:121], off
	v_lshlrev_b32_e32 v124, 16, v64
	v_and_b32_e32 v125, 0xffff0000, v64
	v_lshlrev_b32_e32 v126, 16, v65
	v_and_b32_e32 v127, 0xffff0000, v65
	v_pk_fma_f32 v[2:3], v[112:113], v[2:3], v[124:125] op_sel_hi:[0,1,1]
	v_pk_fma_f32 v[4:5], v[112:113], v[4:5], v[126:127] op_sel_hi:[0,1,1]
	v_cvt_pk_bf16_f32 v122, v2, v3
	v_cvt_pk_bf16_f32 v123, v4, v5
	global_store_dwordx2 v[98:99], v[122:123], off
	v_lshlrev_b32_e32 v124, 16, v66
	v_and_b32_e32 v125, 0xffff0000, v66
	v_lshlrev_b32_e32 v126, 16, v67
	v_and_b32_e32 v127, 0xffff0000, v67
	v_pk_fma_f32 v[2:3], v[114:115], v[2:3], v[124:125] op_sel_hi:[0,1,1]
	v_pk_fma_f32 v[4:5], v[114:115], v[4:5], v[126:127] op_sel_hi:[0,1,1]
	v_cvt_pk_bf16_f32 v120, v2, v3
	v_cvt_pk_bf16_f32 v121, v4, v5
	global_store_dwordx2 v[100:101], v[120:121], off
	v_lshlrev_b32_e32 v124, 16, v68
	v_and_b32_e32 v125, 0xffff0000, v68
	v_lshlrev_b32_e32 v126, 16, v69
	v_and_b32_e32 v127, 0xffff0000, v69
	v_pk_fma_f32 v[2:3], v[116:117], v[2:3], v[124:125] op_sel_hi:[0,1,1]
	v_pk_fma_f32 v[4:5], v[116:117], v[4:5], v[126:127] op_sel_hi:[0,1,1]
	v_cvt_pk_bf16_f32 v122, v2, v3
	v_cvt_pk_bf16_f32 v123, v4, v5
	global_store_dwordx2 v[102:103], v[122:123], off
	v_lshlrev_b32_e32 v124, 16, v70
	v_and_b32_e32 v125, 0xffff0000, v70
	v_lshlrev_b32_e32 v126, 16, v71
	v_and_b32_e32 v127, 0xffff0000, v71
	v_pk_fma_f32 v[2:3], v[118:119], v[2:3], v[124:125] op_sel_hi:[0,1,1]
	v_pk_fma_f32 v[4:5], v[118:119], v[4:5], v[126:127] op_sel_hi:[0,1,1]
	s_add_i32 s18, s18, 1
	s_branch .Lp8_loop
; __device__ __forceinline__ unsigned pk2(float lo, float hi) { const cvt_f2 v = {lo, hi}; const cvt_b2 r = __builtin_convertvector(v, cvt_b2); return __builtin_bit_cast(unsigned, r); }
; __device__ __forceinline__ void ssd_scan_phase(Frame& F, bool dry) {
;     ...
;             for (int i = 0; i < 8; ++i) { v2u o; o.x = pk2(r0, r1); o.y = pk2(r2, r3); *(v2u*)(pd + (size_t)((c0 + i) & cmask) * 524288) = o;
;                 r0 = r0 * dc[i] + bflo(loc[i].x); r1 = r1 * dc[i] + bfhi(loc[i].x); r2 = r2 * dc[i] + bflo(loc[i].y); r3 = r3 * dc[i] + bfhi(loc[i].y); }
;         }
;         if (!dry) { const int e = (i4 * 4) & 8191, blk = e >> 9, ln = (e >> 3) & 63, pn = 16 * (blk >> 2) + (ln & 15), nn = 32 * (blk & 3) + 8 * (ln >> 4) + (e & 7);
;             *(f32x4*)(F.out + O_SSMP + (size_t)h * 8192 + pn * 128 + nn) = (f32x4){r0, r1, r2, r3}; }
.Lp8_last:
	s_waitcnt vmcnt(0)
	v_cvt_pk_bf16_f32 v120, v2, v3
	v_cvt_pk_bf16_f32 v121, v4, v5
	global_store_dwordx2 v[88:89], v[120:121], off
	v_lshlrev_b32_e32 v124, 16, v56
	v_and_b32_e32 v125, 0xffff0000, v56
	v_lshlrev_b32_e32 v126, 16, v57
	v_and_b32_e32 v127, 0xffff0000, v57
	v_pk_fma_f32 v[2:3], v[104:105], v[2:3], v[124:125] op_sel_hi:[0,1,1]
	v_pk_fma_f32 v[4:5], v[104:105], v[4:5], v[126:127] op_sel_hi:[0,1,1]
	v_cvt_pk_bf16_f32 v122, v2, v3
	v_cvt_pk_bf16_f32 v123, v4, v5
	global_store_dwordx2 v[90:91], v[122:123], off
	v_lshlrev_b32_e32 v124, 16, v58
	v_and_b32_e32 v125, 0xffff0000, v58
	v_lshlrev_b32_e32 v126, 16, v59
	v_and_b32_e32 v127, 0xffff0000, v59
	v_pk_fma_f32 v[2:3], v[106:107], v[2:3], v[124:125] op_sel_hi:[0,1,1]
	v_pk_fma_f32 v[4:5], v[106:107], v[4:5], v[126:127] op_sel_hi:[0,1,1]
	v_cvt_pk_bf16_f32 v120, v2, v3
	v_cvt_pk_bf16_f32 v121, v4, v5
	global_store_dwordx2 v[92:93], v[120:121], off
	v_lshlrev_b32_e32 v124, 16, v60
	v_and_b32_e32 v125, 0xffff0000, v60
	v_lshlrev_b32_e32 v126, 16, v61
	v_and_b32_e32 v127, 0xffff0000, v61
	v_pk_fma_f32 v[2:3], v[108:109], v[2:3], v[124:125] op_sel_hi:[0,1,1]
	v_pk_fma_f32 v[4:5], v[108:109], v[4:5], v[126:127] op_sel_hi:[0,1,1]
	v_cvt_pk_bf16_f32 v122, v2, v3
	v_cvt_pk_bf16_f32 v123, v4, v5
	global_store_dwordx2 v[94:95], v[122:123], off
	v_lshlrev_b32_e32 v124, 16, v62
	v_and_b32_e32 v125, 0xffff0000, v62
	v_lshlrev_b32_e32 v126, 16, v63
	v_and_b32_e32 v127, 0xffff0000, v63
	v_pk_fma_f32 v[2:3], v[110:111], v[2:3], v[124:125] op_sel_hi:[0,1,1]
	v_pk_fma_f32 v[4:5], v[110:111], v[4:5], v[126:127] op_sel_hi:[0,1,1]
	v_cvt_pk_bf16_f32 v120, v2, v3
	v_cvt_pk_bf16_f32 v121, v4, v5
	global_store_dwordx2 v[96:97], v[120:121], off
	v_lshlrev_b32_e32 v124, 16, v64
	v_and_b32_e32 v125, 0xffff0000, v64
	v_lshlrev_b32_e32 v126, 16, v65
	v_and_b32_e32 v127, 0xffff0000, v65
	v_pk_fma_f32 v[2:3], v[112:113], v[2:3], v[124:125] op_sel_hi:[0,1,1]
	v_pk_fma_f32 v[4:5], v[112:113], v[4:5], v[126:127] op_sel_hi:[0,1,1]
	v_cvt_pk_bf16_f32 v122, v2, v3
	v_cvt_pk_bf16_f32 v123, v4, v5
	global_store_dwordx2 v[98:99], v[122:123], off
	v_lshlrev_b32_e32 v124, 16, v66
	v_and_b32_e32 v125, 0xffff0000, v66
	v_lshlrev_b32_e32 v126, 16, v67
	v_and_b32_e32 v127, 0xffff0000, v67
	v_pk_fma_f32 v[2:3], v[114:115], v[2:3], v[124:125] op_sel_hi:[0,1,1]
	v_pk_fma_f32 v[4:5], v[114:115], v[4:5], v[126:127] op_sel_hi:[0,1,1]
	v_cvt_pk_bf16_f32 v120, v2, v3
	v_cvt_pk_bf16_f32 v121, v4, v5
	global_store_dwordx2 v[100:101], v[120:121], off
	v_lshlrev_b32_e32 v124, 16, v68
	v_and_b32_e32 v125, 0xffff0000, v68
	v_lshlrev_b32_e32 v126, 16, v69
	v_and_b32_e32 v127, 0xffff0000, v69
	v_pk_fma_f32 v[2:3], v[116:117], v[2:3], v[124:125] op_sel_hi:[0,1,1]
	v_pk_fma_f32 v[4:5], v[116:117], v[4:5], v[126:127] op_sel_hi:[0,1,1]
	v_cvt_pk_bf16_f32 v122, v2, v3
	v_cvt_pk_bf16_f32 v123, v4, v5
	global_store_dwordx2 v[102:103], v[122:123], off
	v_lshlrev_b32_e32 v124, 16, v70
	v_and_b32_e32 v125, 0xffff0000, v70
	v_lshlrev_b32_e32 v126, 16, v71
	v_and_b32_e32 v127, 0xffff0000, v71
	v_pk_fma_f32 v[2:3], v[118:119], v[2:3], v[124:125] op_sel_hi:[0,1,1]
	v_pk_fma_f32 v[4:5], v[118:119], v[4:5], v[126:127] op_sel_hi:[0,1,1]
	v_lshlrev_b32_e32 v1, 2, v6
	v_lshrrev_b32_e32 v7, 2, v6
	v_and_b32_e32 v10, 4, v1
	v_and_or_b32 v7, v7, s7, v10
	v_lshlrev_b32_e32 v10, 6, v6
	v_and_b32_e32 v10, 0x780, v10
	v_lshlrev_b64 v[12:13], 15, v[12:13]
	v_and_or_b32 v1, v1, s16, v10
	v_lshl_add_u64 v[12:13], s[4:5], 0, v[12:13]
	v_lshlrev_b32_e32 v10, 2, v1
	v_add_u32_e32 v6, s6, v6
	v_lshl_add_u64 v[12:13], v[12:13], 0, v[10:11]
	v_lshlrev_b32_e32 v10, 2, v7
	v_cmp_lt_i32_e32 vcc, s17, v6
	v_lshl_add_u64 v[12:13], v[12:13], 0, v[10:11]
	s_or_b64 s[10:11], vcc, s[10:11]
	v_lshl_add_u64 v[8:9], v[8:9], 0, s[8:9]
	global_store_dwordx4 v[12:13], v[2:5], off
	s_andn2_b64 exec, exec, s[10:11]
	s_cbranch_execnz .LBB0_1276
